# stagswap
# baseline (speedup 1.0000x reference)
.LBB0_417:
	s_mov_b32 s22, 0x80
	s_mov_b32 s23, 0
	v_lshl_add_u64 v[124:125], v[50:51], 0, s[22:23]
	v_lshl_add_u64 v[126:127], v[52:53], 0, s[22:23]
	global_load_dwordx4 v[84:87], v[124:125], off
	global_load_dwordx4 v[80:83], v[124:125], off offset:16
	global_load_dwordx4 v[76:79], v[126:127], off
	global_load_dwordx4 v[72:75], v[126:127], off offset:16
	s_waitcnt vmcnt(4) lgkmcnt(0)
	s_barrier
	ds_write_b128 v57, v[46:49]
	ds_write_b128 v57, v[42:45] offset:16
	ds_write_b128 v57, v[38:41] offset:20480
	ds_write_b128 v57, v[34:37] offset:20496
	s_waitcnt lgkmcnt(0)
	s_mov_b32 s22, 0x100
	v_lshl_add_u64 v[124:125], v[50:51], 0, s[22:23]
	v_lshl_add_u64 v[126:127], v[52:53], 0, s[22:23]
	global_load_dwordx4 v[46:49], v[124:125], off
	global_load_dwordx4 v[42:45], v[124:125], off offset:16
	global_load_dwordx4 v[38:41], v[126:127], off
	global_load_dwordx4 v[34:37], v[126:127], off offset:16
	s_barrier
	s_mov_b32 s6, 0
	s_waitcnt vmcnt(4)
	ds_write_b128 v57, v[84:87] offset:40960
	ds_write_b128 v57, v[80:83] offset:40976
	ds_write_b128 v57, v[76:79] offset:61440
	ds_write_b128 v57, v[72:75] offset:61456
	ds_read_b128 v[60:63], v59 offset:20480
	ds_read_b128 v[64:67], v58
	ds_read_b128 v[68:71], v59 offset:23040
	ds_read_b128 v[88:91], v58 offset:2560
	ds_read_b128 v[92:95], v58 offset:5120
	ds_read_b128 v[96:99], v58 offset:7680
	ds_read_b128 v[100:103], v59 offset:20544
	ds_read_b128 v[104:107], v58 offset:64
	ds_read_b128 v[108:111], v59 offset:23104
	ds_read_b128 v[112:115], v58 offset:2624
	ds_read_b128 v[116:119], v58 offset:5184
	ds_read_b128 v[120:123], v58 offset:7744
	s_add_i32 s14, s6, 3
	s_add_i32 s22, s64, -1
	s_min_u32 s14, s14, s22
	s_lshl_b32 s22, s14, 7
	s_waitcnt lgkmcnt(12)
	v_lshl_add_u64 v[124:125], v[50:51], 0, s[22:23]
	v_lshl_add_u64 v[126:127], v[52:53], 0, s[22:23]
	global_load_dwordx4 v[84:87], v[124:125], off
	global_load_dwordx4 v[80:83], v[124:125], off offset:16
	global_load_dwordx4 v[76:79], v[126:127], off
	global_load_dwordx4 v[72:75], v[126:127], off offset:16
	s_waitcnt lgkmcnt(0)
	s_barrier
	v_readfirstlane_b32 s14, v167
	s_lshr_b32 s14, s14, 8
	s_cmp_eq_u32 s14, 0
	s_cbranch_scc1 .Lsrt_loop_b
